# attention tile loop: 15 packed v_pk_mul_f32 accumulator rescales split into scalar v_mul_f32 pairs (packed fp32 ops between MFMAs stall issue longer than the two scalar ops)
# speedup vs baseline: 1.0030x; 1.0002x over previous
; DEVI unsigned pk2(float lo, float hi) { f32x2 v = {lo, hi}; bf16x2_t b = __builtin_convertvector(v, bf16x2_t); return __builtin_bit_cast(unsigned, b); }
; DEVI void attn_item(const P& p, int item, char* smem) {
;     ...
;                 float mx = s[0][0];
; #pragma unroll
;                 for (int n = 0; n < 4; ++n)
; #pragma unroll
;                     for (int j = 0; j < 4; ++j) mx = fmaxf(mx, s[n][j]);
;                 mx = rowmax4(mx);
;                 const float mnew = fmaxf(mrow[m], mx);
;                 const float alpha = __builtin_amdgcn_exp2f(mrow[m] - mnew);
;                 mrow[m] = mnew;
;                 float ls = 0.f;
; #pragma unroll
;                 for (int n = 0; n < 4; ++n)
; #pragma unroll
;                     for (int j = 0; j < 4; ++j) { s[n][j] = __builtin_amdgcn_exp2f(s[n][j] - mnew); ls += s[n][j]; }
;                 lrow[m] = lrow[m] * alpha + ls;
; #pragma unroll
;                 for (int nd = 0; nd < 4; ++nd) O[nd][m] *= alpha;
; #pragma unroll
;                 for (int kk = 0; kk < 2; ++kk) {
;                     union { uint4 u; bf16x8 v; } cv;
;                     cv.u.x = pk2(s[2 * kk][0], s[2 * kk][1]); cv.u.y = pk2(s[2 * kk][2], s[2 * kk][3]);
;                     cv.u.z = pk2(s[2 * kk + 1][0], s[2 * kk + 1][1]); cv.u.w = pk2(s[2 * kk + 1][2], s[2 * kk + 1][3]);
;                     Pf[m][kk] = cv.v;
;                 }
;             }
; #pragma unroll
;             for (int nd = 0; nd < 4; ++nd)
; #pragma unroll
;                 for (int kk = 0; kk < 2; ++kk) {
;                     const int row = 16 * nd + fr, x2 = 2 * ((row >> 1) & 7);
;                     const uint2 lo = *(const uint2*)(sV + row * 128 + (((8 * kk + fq) ^ x2) << 3));
;                     const uint2 hi = *(const uint2*)(sV + row * 128 + (((8 * kk + 4 + fq) ^ x2) << 3));
;                     union { uint4 u; bf16x8 v; } cv;
;                     cv.u.x = lo.x; cv.u.y = lo.y; cv.u.z = hi.x; cv.u.w = hi.y;
; #pragma unroll
;                     for (int m = 0; m < 2; ++m) O[nd][m] = __builtin_amdgcn_mfma_f32_16x16x32_bf16(cv.v, Pf[m][kk], O[nd][m], 0, 0, 0);
.LBB0_1433:
	v_max3_f32 v91, v160, v86, v87
	v_sub_f32_e32 v0, v78, v91
	v_exp_f32_e32 v78, v0
	v_sub_f32_e32 v79, v79, v91
	v_exp_f32_e32 v79, v79
	v_sub_f32_e32 v80, v80, v91
	v_exp_f32_e32 v80, v80
	v_sub_f32_e32 v81, v81, v91
	v_exp_f32_e32 v81, v81
	v_sub_f32_e32 v74, v74, v91
	v_add_f32_e32 v82, 0, v78
	v_exp_f32_e32 v74, v74
	v_sub_f32_e32 v75, v75, v91
	v_add_f32_e32 v82, v79, v82
	v_exp_f32_e32 v75, v75
	v_sub_f32_e32 v76, v76, v91
	v_add_f32_e32 v82, v80, v82
	v_exp_f32_e32 v76, v76
	v_sub_f32_e32 v77, v77, v91
	v_add_f32_e32 v82, v81, v82
	v_exp_f32_e32 v77, v77
	v_sub_f32_e32 v58, v58, v91
	v_add_f32_e32 v82, v74, v82
	v_exp_f32_e32 v58, v58
	v_sub_f32_e32 v59, v59, v91
	v_add_f32_e32 v82, v75, v82
	v_exp_f32_e32 v59, v59
	v_add_f32_e32 v82, v76, v82
	v_add_f32_e32 v82, v77, v82
	v_add_f32_e32 v82, v58, v82
	v_sub_f32_e32 v50, v50, v91
	v_sub_f32_e32 v51, v51, v91
	v_exp_f32_e32 v83, v50
	v_add_f32_e32 v50, v59, v82
	v_exp_f32_e32 v82, v51
	v_sub_f32_e32 v51, v52, v91
	v_cvt_pk_bf16_f32 v52, v74, v75
	v_max_f32_e32 v74, v70, v71
	v_max3_f32 v74, v74, v72, v73
	v_max3_f32 v74, v74, v62, v63
	v_max3_f32 v74, v74, v64, v65
	v_max3_f32 v74, v74, v54, v55
	v_sub_f32_e32 v60, v60, v91
	v_max3_f32 v74, v74, v56, v57
	v_exp_f32_e32 v60, v60
	v_sub_f32_e32 v61, v61, v91
	v_max3_f32 v74, v74, v66, v67
	v_exp_f32_e32 v61, v61
	v_max3_f32 v74, v74, v68, v69
	v_mov_b32_e32 v75, v74
	s_nop 1
	v_permlane32_swap_b32_e32 v74, v75
	v_add_f32_e32 v50, v60, v50
	v_exp_f32_e32 v84, v51
	v_sub_f32_e32 v51, v53, v91
	v_sub_f32_e32 v0, v160, v91
	v_add_f32_e32 v50, v61, v50
	v_exp_f32_e32 v85, v51
	v_max_f32_e32 v74, v74, v75
	v_add_f32_e32 v50, v83, v50
	v_exp_f32_e32 v0, v0
	v_mov_b32_e32 v75, v74
	v_add_f32_e32 v50, v82, v50
	s_nop 0
	v_permlane16_swap_b32_e32 v74, v75
	v_add_f32_e32 v50, v84, v50
	v_max3_f32 v93, v159, v74, v75
	v_add_f32_e32 v92, v85, v50
	v_sub_f32_e32 v54, v54, v93
	v_fmac_f32_e32 v92, v158, v0
	v_exp_f32_e32 v158, v54
	v_sub_f32_e32 v54, v55, v93
	v_sub_f32_e32 v74, v159, v93
	v_exp_f32_e32 v159, v54
	v_sub_f32_e32 v54, v56, v93
	v_exp_f32_e32 v160, v54
	v_sub_f32_e32 v54, v57, v93
	v_sub_f32_e32 v62, v62, v93
	v_exp_f32_e32 v161, v54
	v_sub_f32_e32 v54, v66, v93
	v_exp_f32_e32 v94, v62
	v_sub_f32_e32 v62, v63, v93
	v_exp_f32_e32 v162, v54
	v_sub_f32_e32 v54, v67, v93
	v_exp_f32_e32 v95, v62
	v_sub_f32_e32 v62, v64, v93
	v_exp_f32_e32 v163, v54
	v_sub_f32_e32 v54, v68, v93
	v_exp_f32_e32 v96, v62
	v_sub_f32_e32 v62, v65, v93
	v_exp_f32_e32 v164, v54
	v_sub_f32_e32 v54, v69, v93
	v_exp_f32_e32 v97, v62
	v_exp_f32_e32 v165, v54
	ds_read_b128 v[54:57], v132 offset:8192
	ds_read_b128 v[62:65], v132 offset:10240
	v_sub_f32_e32 v70, v70, v93
	v_exp_f32_e32 v86, v70
	v_sub_f32_e32 v70, v71, v93
	v_exp_f32_e32 v87, v70
	v_sub_f32_e32 v70, v72, v93
	v_cvt_pk_bf16_f32 v50, v78, v79
	v_cvt_pk_bf16_f32 v51, v80, v81
	v_cvt_pk_bf16_f32 v53, v76, v77
	v_exp_f32_e32 v88, v70
	v_sub_f32_e32 v70, v73, v93
	v_exp_f32_e32 v90, v74
	ds_read_b128 v[74:77], v134 offset:8192
	ds_read_b128 v[78:81], v134 offset:10240
	v_exp_f32_e32 v89, v70
	s_waitcnt lgkmcnt(3)
	s_waitcnt lgkmcnt(2)
	v_mul_f32_e32 v40, v0, v40
	v_mul_f32_e32 v41, v0, v41
	v_mul_f32_e32 v38, v0, v38
	v_mul_f32_e32 v39, v0, v39
	v_mul_f32_e32 v44, v0, v44
	v_mul_f32_e32 v45, v0, v45
	v_mul_f32_e32 v42, v0, v42
	v_mul_f32_e32 v43, v0, v43
	v_cvt_pk_bf16_f32 v58, v58, v59
	v_cvt_pk_bf16_f32 v59, v60, v61
	v_cvt_pk_bf16_f32 v60, v83, v82
	v_cvt_pk_bf16_f32 v61, v84, v85
	v_mul_f32_e32 v16, v90, v16
	v_mul_f32_e32 v17, v90, v17
	v_mul_f32_e32 v14, v90, v14
	v_mul_f32_e32 v15, v90, v15
	v_cvt_pk_bf16_f32 v66, v86, v87
	v_cvt_pk_bf16_f32 v67, v88, v89
	v_cvt_pk_bf16_f32 v68, v94, v95
	v_cvt_pk_bf16_f32 v69, v96, v97
	s_waitcnt lgkmcnt(1)
	s_waitcnt lgkmcnt(0)
	v_mul_f32_e32 v12, v90, v12
	v_mul_f32_e32 v13, v90, v13
	v_mul_f32_e32 v10, v90, v10
	v_mul_f32_e32 v11, v90, v11
	v_mul_f32_e32 v48, v0, v48
	v_mul_f32_e32 v49, v0, v49
	v_mul_f32_e32 v46, v0, v46
	v_mul_f32_e32 v47, v0, v47
	v_mfma_f32_16x16x32_bf16 v[38:41], v[54:57], v[50:53], v[38:41]
	v_mul_f32_e64 v20, v20, v0
	v_mul_f32_e64 v21, v21, v0
	v_mul_f32_e32 v18, v0, v18
	v_mul_f32_e32 v19, v0, v19
	v_add_f32_e32 v0, 0, v86
	v_mfma_f32_16x16x32_bf16 v[14:17], v[54:57], v[66:69], v[14:17]
	ds_read_b128 v[54:57], v132 offset:12288
	v_add_f32_e32 v0, v87, v0
	v_add_f32_e32 v0, v88, v0
	v_mfma_f32_16x16x32_bf16 v[42:45], v[62:65], v[50:53], v[42:45]
	v_cvt_pk_bf16_f32 v70, v158, v159
	v_cvt_pk_bf16_f32 v71, v160, v161
	v_cvt_pk_bf16_f32 v72, v162, v163
	v_mfma_f32_16x16x32_bf16 v[10:13], v[62:65], v[66:69], v[10:13]
	ds_read_b128 v[62:65], v132 offset:14336
	v_cvt_pk_bf16_f32 v73, v164, v165
	v_add_f32_e32 v0, v89, v0
	v_mfma_f32_16x16x32_bf16 v[38:41], v[74:77], v[58:61], v[38:41]
	v_add_f32_e32 v0, v94, v0
	s_waitcnt lgkmcnt(1)
	v_mfma_f32_16x16x32_bf16 v[14:17], v[74:77], v[70:73], v[14:17]
	ds_read_b128 v[74:77], v134 offset:12288
	s_waitcnt lgkmcnt(1)
	v_mfma_f32_16x16x32_bf16 v[42:45], v[78:81], v[58:61], v[42:45]
	v_add_f32_e32 v0, v95, v0
	v_mfma_f32_16x16x32_bf16 v[10:13], v[78:81], v[70:73], v[10:13]
	ds_read_b128 v[78:81], v134 offset:14336
	v_add_f32_e32 v0, v96, v0
	v_add_f32_e32 v0, v97, v0
	v_add_f32_e32 v0, v158, v0
	v_mul_f32_e32 v8, v90, v8
	v_mul_f32_e32 v9, v90, v9
	v_mul_f32_e32 v6, v90, v6
	v_mul_f32_e32 v7, v90, v7
	s_waitcnt lgkmcnt(0)
	v_xor_b32_e32 v133, 0x4000, v133
	v_xor_b32_e32 v135, 0x4000, v135
	v_xor_b32_e32 v214, 0x4000, v214
	v_xor_b32_e32 v217, 0x4000, v217
	v_xor_b32_e32 v229, 0x4000, v229
	v_xor_b32_e32 v215, 0x4000, v215
	s_cmp_eq_u32 s99, 1
	s_cbranch_scc0 .Lat_endw2
	s_waitcnt vmcnt(0)
	ds_write_b128 v133, v[190:193]
	ds_write_b64 v135, v[194:195] offset:8192
	ds_write_b64 v214, v[196:197] offset:8192
	ds_write_b128 v217, v[198:201]
	ds_write_b64 v229, v[202:203] offset:8192
	ds_write_b64 v215, v[204:205] offset:8192
	s_mov_b32 s99, 2
.Lat_endw2:
	v_add_f32_e32 v0, v159, v0
	v_mul_f32_e32 v4, v90, v4
	v_mul_f32_e32 v5, v90, v5
	v_mul_f32_e32 v2, v90, v2
	v_mul_f32_e32 v3, v90, v3
	v_mfma_f32_16x16x32_bf16 v[46:49], v[54:57], v[50:53], v[46:49]
	v_add_f32_e32 v0, v160, v0
	v_add_f32_e32 v0, v161, v0
	v_add_f32_e32 v0, v162, v0
	v_mfma_f32_16x16x32_bf16 v[6:9], v[54:57], v[66:69], v[6:9]
	v_add_f32_e32 v0, v163, v0
	v_add_f32_e32 v0, v164, v0
	v_add_f32_e32 v0, v165, v0
	v_mfma_f32_16x16x32_bf16 v[18:21], v[62:65], v[50:53], v[18:21]
	v_fmac_f32_e32 v0, v139, v90
	v_mov_b32_e32 v159, v93
	v_mov_b32_e32 v160, v91
	v_mfma_f32_16x16x32_bf16 v[2:5], v[62:65], v[66:69], v[2:5]
	v_mov_b32_e32 v139, v0
	v_mov_b32_e32 v158, v92
	v_mfma_f32_16x16x32_bf16 v[46:49], v[74:77], v[58:61], v[46:49]
	v_mfma_f32_16x16x32_bf16 v[6:9], v[74:77], v[70:73], v[6:9]
	v_mfma_f32_16x16x32_bf16 v[18:21], v[78:81], v[58:61], v[18:21]
	v_mfma_f32_16x16x32_bf16 v[2:5], v[78:81], v[70:73], v[2:5]
	v_xor_b32_e32 v130, 0x4000, v130
	v_xor_b32_e32 v131, 0x4000, v131
	v_xor_b32_e32 v132, 0x4000, v132
	v_xor_b32_e32 v134, 0x4000, v134
